# tile order: output-projection GEMM also 4 row panels x 8 column tiles per XCD step (on top of the FFN-down remap)
# speedup vs baseline: 1.0126x; 1.0010x over previous
;     __host__ __device__ __forceinline__ bool next(int i, Unit& u) const {
;         const long L = (long)i * G + c; if (L >= nwg) return false;
;         int wgid = (int)L; { const int q = nwg / NXCD, r = nwg % NXCD, xcd = wgid % NXCD, off = wgid / NXCD; wgid = (xcd < r ? xcd * (q + 1) : r * (q + 1) + (xcd - r) * q) + off; }
;         const int nig = WGM * nN, gid = wgid / nig, fm = gid * WGM, gsz = (nM - fm) < WGM ? (nM - fm) : WGM;
;         u.pm = fm + ((wgid % nig) % gsz); u.pn = (wgid % nig) / gsz; return true;
;     }
.LBB0_1010:
	s_ashr_i32 s1, s1, 3
	s_add_i32 s1, s11, s1
	s_ashr_i32 s6, s1, 31
	s_lshr_b32 s6, s6, 26
	s_add_i32 s6, s1, s6
	s_ashr_i32 s7, s6, 6
	s_and_b32 s6, s6, 0xffc0
	s_sub_i32 s1, s1, s6
	s_bfe_i32 s6, s1, 0x80000
	s_bfe_u32 s6, s6, 0x3000c
	s_add_i32 s6, s1, s6
	s_bfe_i32 s10, s6, 0x80000
	s_and_b32 s6, s6, 0xf8
	s_sub_i32 s1, s1, s6
	s_lshl_b32 s7, s7, 3
	s_sext_i32_i16 s10, s10
	s_sext_i32_i8 s1, s1
	s_add_i32 s22, s7, s1
	s_ashr_i32 s6, s10, 3
	s_lshr_b32 s1, s6, 2
	s_lshl_b32 s1, s1, 2
	s_and_b32 s7, s22, 3
	s_add_i32 s1, s1, s7
	s_bfe_u32 s7, s22, 0x10002
	s_and_b32 s6, s6, 3
	s_lshl_b32 s6, s6, 1
	s_add_i32 s6, s6, s7
	s_and_b32 s22, s22, -8
	s_add_i32 s22, s22, s1

;     __host__ __device__ __forceinline__ bool next(int i, Unit& u) const {
;         const long L = (long)i * G + c; if (L >= nwg) return false;
;         int wgid = (int)L; { const int q = nwg / NXCD, r = nwg % NXCD, xcd = wgid % NXCD, off = wgid / NXCD; wgid = (xcd < r ? xcd * (q + 1) : r * (q + 1) + (xcd - r) * q) + off; }
;         const int nig = WGM * nN, gid = wgid / nig, fm = gid * WGM, gsz = (nM - fm) < WGM ? (nM - fm) : WGM;
;         u.pm = fm + ((wgid % nig) % gsz); u.pn = (wgid % nig) / gsz; return true;
;     }
;     ...
;         const bool has_next = S.next(ui + 1, nxt);
.LBB0_1022:
	s_ashr_i32 s7, s7, 3
	s_add_i32 s7, s17, s7
	s_ashr_i32 s14, s7, 31
	s_lshr_b32 s14, s14, 26
	s_add_i32 s14, s7, s14
	s_ashr_i32 s15, s14, 6
	s_lshl_b32 s15, s15, 3
	s_sub_i32 s16, 64, s15
	s_min_i32 s16, s16, 8
	s_abs_i32 s17, s16
	v_cvt_f32_u32_e32 v2, s17
	s_sub_i32 s19, 0, s17
	s_andn2_b32 s14, s14, 63
	s_sub_i32 s7, s7, s14
	v_rcp_iflag_f32_e32 v2, v2
	s_abs_i32 s14, s7
	s_xor_b32 s18, s7, s16
	s_ashr_i32 s18, s18, 31
	v_mul_f32_e32 v2, 0x4f7ffffe, v2
	v_cvt_u32_f32_e32 v2, v2
	s_nop 0
	v_readfirstlane_b32 s20, v2
	s_mul_i32 s19, s19, s20
	s_mul_hi_u32 s19, s20, s19
	s_add_i32 s20, s20, s19
	s_mul_hi_u32 s19, s14, s20
	s_mul_i32 s20, s19, s17
	s_sub_i32 s14, s14, s20
	s_add_i32 s21, s19, 1
	s_sub_i32 s20, s14, s17
	s_cmp_ge_u32 s14, s17
	s_cselect_b32 s19, s21, s19
	s_cselect_b32 s14, s20, s14
	s_add_i32 s20, s19, 1
	s_cmp_ge_u32 s14, s17
	s_cselect_b32 s14, s20, s19
	s_xor_b32 s14, s14, s18
	s_sub_i32 s14, s14, s18
	s_mul_i32 s16, s14, s16
	s_sub_i32 s7, s7, s16
	s_add_i32 s16, s15, s7
	s_lshr_b32 s18, s14, 2
	s_lshl_b32 s18, s18, 2
	s_and_b32 s19, s16, 3
	s_add_i32 s18, s18, s19
	s_bfe_u32 s19, s16, 0x10002
	s_and_b32 s14, s14, 3
	s_lshl_b32 s14, s14, 1
	s_add_i32 s14, s14, s19
	s_and_b32 s16, s16, -8
	s_add_i32 s16, s16, s18
